# layer-1 MLP1 weight conversion moved off the critical path: done by workgroups 64.. in the cmp phase (idle there) instead of by all workgroups before PROJ/GATE
# baseline (speedup 1.0000x reference)
.LBB0_690:
	s_load_dwordx4 s[4:7], s[0:1], 0x78
	s_waitcnt lgkmcnt(0)
	v_writelane_b32 v232, s4, 21
	v_writelane_b32 v232, s5, 22
	v_writelane_b32 v232, s6, 23
	v_writelane_b32 v232, s7, 24
	s_branch .LBB0_702
	v_mov_b32_e32 v0, v136
	s_and_b64 vcc, exec, s[10:11]
	s_cbranch_vccnz .LBB0_702
	s_load_dwordx4 s[4:7], s[0:1], 0x78
	v_ashrrev_i32_e32 v9, 3, v0
	v_lshlrev_b32_e32 v0, 3, v0
	v_and_b32_e32 v8, 56, v0
	v_lshl_add_u32 v2, v9, 2, 16
	s_waitcnt lgkmcnt(0)
	s_add_u32 s16, s6, 0x4000000
	s_addc_u32 s17, s7, 0
	s_add_u32 s18, s4, 0x2000
	s_addc_u32 s19, s5, 0
	s_add_u32 s20, s52, 0x2800000
	s_addc_u32 s21, s53, 0
	s_cmp_lg_u64 s[4:5], 0
	s_cselect_b64 s[6:7], -1, 0
	s_movk_i32 s4, 0x104
	v_mul_u32_u24_e32 v3, 0x104, v8
	v_lshl_add_u32 v0, v8, 2, 16
	v_mul_lo_u32 v1, v9, s4
	v_cndmask_b32_e64 v4, 0, 1, s[6:7]
	v_add_u32_e32 v18, v2, v3
	v_mov_b32_e32 v11, 0
	s_lshl_b32 s4, s2, 6
	s_lshl_b32 s5, s34, 6
	v_cmp_ne_u32_e64 s[14:15], 1, v4
	s_movk_i32 s6, 0x2000
	v_add_u32_e32 v13, v0, v1
	v_lshlrev_b32_e32 v10, 1, v8
	v_add_u32_e32 v19, 0x400, v18
	s_mov_b32 s7, s2
	s_branch .LBB0_693

.Lgate_skip:
	s_cmp_lt_u32 s2, 64
	s_cbranch_scc1 .Lmv1_skip
	s_sub_i32 s60, s2, 64
	s_sub_i32 s61, s34, 64
	v_mov_b32_e32 v0, v136
	v_readlane_b32 s4, v232, 21
	v_readlane_b32 s5, v232, 22
	v_readlane_b32 s6, v232, 23
	v_readlane_b32 s7, v232, 24
	s_nop 3
	v_ashrrev_i32_e32 v9, 3, v0
	v_lshlrev_b32_e32 v0, 3, v0
	v_and_b32_e32 v8, 56, v0
	v_lshl_add_u32 v2, v9, 2, 16
	s_waitcnt lgkmcnt(0)
	s_add_u32 s16, s6, 0x4000000
	s_addc_u32 s17, s7, 0
	s_add_u32 s18, s4, 0x2000
	s_addc_u32 s19, s5, 0
	s_add_u32 s20, s30, 0x2800000
	s_addc_u32 s21, s31, 0
	s_cmp_lg_u64 s[4:5], 0
	s_cselect_b64 s[6:7], -1, 0
	s_movk_i32 s4, 0x104
	v_mul_u32_u24_e32 v3, 0x104, v8
	v_lshl_add_u32 v0, v8, 2, 16
	v_mul_lo_u32 v1, v9, s4
	v_cndmask_b32_e64 v4, 0, 1, s[6:7]
	v_add_u32_e32 v18, v2, v3
	v_mov_b32_e32 v11, 0
	s_lshl_b32 s4, s60, 6
	s_lshl_b32 s5, s61, 6
	v_cmp_ne_u32_e64 s[14:15], 1, v4
	s_movk_i32 s6, 0x2000
	v_add_u32_e32 v13, v0, v1
	v_lshlrev_b32_e32 v10, 1, v8
	v_add_u32_e32 v19, 0x400, v18
	s_mov_b32 s7, s60
	s_branch .Lmv1_693
.Lmv1_692:
	s_or_b64 exec, exec, s[62:63]
	s_add_i32 s7, s7, s61
	s_add_i32 s4, s4, s5
	s_cmpk_lt_i32 s7, 0x1000
	s_barrier
	s_cbranch_scc0 .Lmv1_done

.Lmv1_696:
	s_lshl_b32 s8, s8, 13
	s_sub_i32 s9, s4, s8
	v_add_u32_e32 v16, s9, v8
	v_cmp_gt_i32_e32 vcc, s6, v16
	v_mov_b32_e32 v0, 0
	v_ashrrev_i32_e32 v17, 31, v16
	v_mov_b32_e32 v4, 0
	v_mov_b32_e32 v5, 0
	v_mov_b32_e32 v6, 0
	v_mov_b32_e32 v7, 0
	s_and_saveexec_b64 s[62:63], vcc
	s_cbranch_execz .Lmv1_698
	v_lshlrev_b64 v[2:3], 15, v[14:15]
	v_lshl_add_u64 v[2:3], s[16:17], 0, v[2:3]
	v_lshl_add_u64 v[2:3], v[16:17], 2, v[2:3]
	global_load_dwordx4 v[4:7], v[2:3], off
.Lmv1_698:
	s_or_b64 exec, exec, s[62:63]
	v_add_u32_e32 v1, 4, v16
	v_cmp_gt_i32_e32 vcc, s6, v1
	v_mov_b32_e32 v1, 0
	v_mov_b32_e32 v2, 0
	v_mov_b32_e32 v3, 0
	s_and_saveexec_b64 s[62:63], vcc
	s_cbranch_execz .Lmv1_700
	v_lshlrev_b64 v[0:1], 15, v[14:15]
	v_lshl_add_u64 v[0:1], s[16:17], 0, v[0:1]
	v_lshl_add_u64 v[0:1], v[16:17], 2, v[0:1]
	global_load_dwordx4 v[0:3], v[0:1], off offset:16
.Lmv1_700:
	s_or_b64 exec, exec, s[62:63]
	s_waitcnt vmcnt(0)
	v_pk_mul_f32 v[0:1], v[12:13], v[0:1] op_sel_hi:[0,1]
	s_sub_i32 s8, 0, s8
	ds_write2_b32 v13, v0, v1 offset0:4 offset1:5
	v_pk_mul_f32 v[0:1], v[12:13], v[6:7] op_sel_hi:[0,1]
	ds_write2_b32 v13, v0, v1 offset0:2 offset1:3
	v_pk_mul_f32 v[0:1], v[12:13], v[2:3] op_sel_hi:[0,1]
	s_add_i32 s8, s8, s4
	ds_write2_b32 v13, v0, v1 offset0:6 offset1:7
	v_add_u32_e32 v0, s8, v9
	v_pk_mul_f32 v[4:5], v[12:13], v[4:5] op_sel_hi:[0,1]
	v_cmp_gt_i32_e32 vcc, s6, v0
	ds_write2_b32 v13, v4, v5 offset1:1
	s_waitcnt lgkmcnt(0)
	s_barrier
	s_and_saveexec_b64 s[62:63], vcc
	s_cbranch_execz .Lmv1_692
	ds_read2_b32 v[2:3], v18 offset1:65
	ds_read2_b32 v[4:5], v18 offset0:130 offset1:195
	ds_read2_b32 v[6:7], v19 offset0:4 offset1:69
	ds_read2_b32 v[14:15], v19 offset0:134 offset1:199
	v_ashrrev_i32_e32 v1, 31, v0
	v_lshlrev_b64 v[0:1], 12, v[0:1]
	v_lshl_add_u64 v[0:1], s[20:21], 0, v[0:1]
	s_ashr_i32 s23, s22, 31
	v_lshl_add_u64 v[0:1], s[22:23], 1, v[0:1]
	s_waitcnt lgkmcnt(3)
	v_cvt_pk_bf16_f32 v2, v2, v3
	s_waitcnt lgkmcnt(2)
	v_cvt_pk_bf16_f32 v3, v4, v5
	s_waitcnt lgkmcnt(1)
	v_cvt_pk_bf16_f32 v4, v6, v7
	s_waitcnt lgkmcnt(0)
	v_cvt_pk_bf16_f32 v5, v14, v15
	v_lshl_add_u64 v[0:1], v[0:1], 0, v[10:11]
	global_store_dwordx4 v[0:1], v[2:5], off
	s_branch .Lmv1_692
.Lmv1_done:
	v_mov_b32_e32 v8, v136
.Lmv1_skip:
	s_cmp_gt_i32 s38, 31
	v_readfirstlane_b32 s4, v8
	s_cbranch_scc1 .LBB0_1279
	s_ashr_i32 s5, s38, 31
	s_lshr_b32 s6, s5, 29
	s_add_i32 s6, s38, s6
	s_and_b32 s7, s6, -8
	s_sub_i32 s7, s38, s7
	s_cmp_gt_i32 s7, -1
	s_cbranch_scc0 .LBB0_1262
	s_lshl_b32 s9, s7, 2
	s_cbranch_execz .LBB0_1263
	s_branch .LBB0_1264
